# back-edge rotation (guide 7.11) on FFN1 and FFN2 k-loops: counter/pointer updates and next-iteration scalar selects moved ahead of the loop-back barrier, exit path has its own barrier
# baseline (speedup 1.0000x reference)
.LBB0_1137:
	s_ashr_i32 s37, s36, 31
	s_lshl_b64 s[18:19], s[36:37], 19
	s_add_u32 s40, s96, s18
	s_addc_u32 s41, s97, s19
	s_and_b64 s[18:19], s[42:43], exec
	s_cselect_b32 s17, s41, s59
	s_cselect_b32 s37, s40, s58
	s_ashr_i32 s39, s38, 31
	s_lshl_b64 s[18:19], s[38:39], 19
	s_add_u32 s48, s5, s18
	s_addc_u32 s49, s6, s19
	s_and_b64 s[18:19], s[42:43], exec
	s_cselect_b32 s39, s49, s51
	s_cselect_b32 s46, s48, s50
	s_add_u32 s58, s58, 0x40080
	s_addc_u32 s59, s59, 0
	s_add_u32 s47, s50, 0x100
	s_addc_u32 s62, s51, 0
	s_mov_b32 s63, -2
	s_add_u32 s18, s58, 0xfffc0080
	s_addc_u32 s19, s59, -1
	s_add_i32 s20, 0, 0x10000
	s_cmp_eq_u32 s63, 12
	s_cselect_b32 s61, s17, s19
	s_cselect_b32 s60, s37, s18
	v_add_u32_e32 v140, s20, v143
	s_cselect_b32 s51, s39, s62
	s_cselect_b32 s50, s46, s47
	s_add_i32 s21, 0, 0x14000
	ds_read_b128 v[146:149], v140
	ds_read_b128 v[150:153], v140 offset:1024
	ds_read_b128 v[154:157], v140 offset:2048
	ds_read_b128 v[164:167], v140 offset:3072
	v_add_u32_e32 v140, s21, v143
	ds_read_b128 v[168:171], v140
	ds_read_b128 v[172:175], v140 offset:1024
	ds_read_b128 v[176:179], v140 offset:2048
	ds_read_b128 v[180:183], v140 offset:3072
	v_lshl_add_u64 v[140:141], s[58:59], 0, v[136:137]
	s_add_i32 m0, s8, 0xc000
	ds_read_b128 v[184:187], v144
	ds_read_b128 v[188:191], v144 offset:1024
	ds_read_b128 v[192:195], v144 offset:2048
	ds_read_b128 v[196:199], v144 offset:3072
	ds_read_b128 v[206:209], v144 offset:4096
	ds_read_b128 v[210:213], v144 offset:5120
	ds_read_b128 v[214:217], v144 offset:6144
	ds_read_b128 v[218:221], v144 offset:7168
	global_load_lds_dwordx4 v[140:141], off
	v_lshl_add_u64 v[140:141], s[58:59], 0, v[138:139]
	s_add_i32 m0, s8, 0xe000
	s_nop 0
	global_load_lds_dwordx4 v[140:141], off
	s_waitcnt vmcnt(8)
	s_waitcnt lgkmcnt(0)
	s_barrier
	s_setprio 1
	s_waitcnt lgkmcnt(0)
	v_mfma_f32_16x16x32_bf16 v[124:127], v[146:149], v[184:187], 0
	v_mfma_f32_16x16x32_bf16 v[120:123], v[154:157], v[184:187], 0
	v_mfma_f32_16x16x32_bf16 v[108:111], v[146:149], v[192:195], 0
	v_mfma_f32_16x16x32_bf16 v[104:107], v[154:157], v[192:195], 0
	v_mfma_f32_16x16x32_bf16 v[92:95], v[146:149], v[206:209], 0
	v_mfma_f32_16x16x32_bf16 v[88:91], v[154:157], v[206:209], 0
	v_mfma_f32_16x16x32_bf16 v[76:79], v[146:149], v[214:217], 0
	v_mfma_f32_16x16x32_bf16 v[72:75], v[154:157], v[214:217], 0
	v_mfma_f32_16x16x32_bf16 v[124:127], v[150:153], v[188:191], v[124:127]
	v_mfma_f32_16x16x32_bf16 v[120:123], v[164:167], v[188:191], v[120:123]
	v_mfma_f32_16x16x32_bf16 v[108:111], v[150:153], v[196:199], v[108:111]
	v_mfma_f32_16x16x32_bf16 v[104:107], v[164:167], v[196:199], v[104:107]
	v_mfma_f32_16x16x32_bf16 v[92:95], v[150:153], v[210:213], v[92:95]
	v_mfma_f32_16x16x32_bf16 v[88:91], v[164:167], v[210:213], v[88:91]
	v_mfma_f32_16x16x32_bf16 v[76:79], v[150:153], v[218:221], v[76:79]
	v_mfma_f32_16x16x32_bf16 v[72:75], v[164:167], v[218:221], v[72:75]
	s_setprio 0
	s_setprio 1
	v_mfma_f32_16x16x32_bf16 v[116:119], v[168:171], v[184:187], 0
	v_mfma_f32_16x16x32_bf16 v[112:115], v[176:179], v[184:187], 0
	v_mfma_f32_16x16x32_bf16 v[100:103], v[168:171], v[192:195], 0
	v_mfma_f32_16x16x32_bf16 v[96:99], v[176:179], v[192:195], 0
	v_mfma_f32_16x16x32_bf16 v[84:87], v[168:171], v[206:209], 0
	v_mfma_f32_16x16x32_bf16 v[80:83], v[176:179], v[206:209], 0
	v_mfma_f32_16x16x32_bf16 v[68:71], v[168:171], v[214:217], 0
	v_mfma_f32_16x16x32_bf16 v[64:67], v[176:179], v[214:217], 0
	v_mfma_f32_16x16x32_bf16 v[116:119], v[172:175], v[188:191], v[116:119]
	v_mfma_f32_16x16x32_bf16 v[112:115], v[180:183], v[188:191], v[112:115]
	v_mfma_f32_16x16x32_bf16 v[100:103], v[172:175], v[196:199], v[100:103]
	v_mfma_f32_16x16x32_bf16 v[96:99], v[180:183], v[196:199], v[96:99]
	v_mfma_f32_16x16x32_bf16 v[84:87], v[172:175], v[210:213], v[84:87]
	v_mfma_f32_16x16x32_bf16 v[80:83], v[180:183], v[210:213], v[80:83]
	v_mfma_f32_16x16x32_bf16 v[68:71], v[172:175], v[218:221], v[68:71]
	v_mfma_f32_16x16x32_bf16 v[64:67], v[180:183], v[218:221], v[64:67]
	s_setprio 0
	s_barrier
	s_add_i32 s18, s20, s7
	v_lshl_add_u64 v[140:141], s[50:51], 0, v[132:133]
	s_mov_b32 m0, s18
	ds_read_b128 v[184:187], v144 offset:16384
	ds_read_b128 v[188:191], v144 offset:17408
	ds_read_b128 v[192:195], v144 offset:18432
	ds_read_b128 v[196:199], v144 offset:19456
	ds_read_b128 v[206:209], v144 offset:20480
	ds_read_b128 v[210:213], v144 offset:21504
	ds_read_b128 v[214:217], v144 offset:22528
	ds_read_b128 v[218:221], v144 offset:23552
	global_load_lds_dwordx4 v[140:141], off
	s_add_i32 m0, s18, 0x2000
	s_add_u32 s18, s50, 0x40000
	v_lshl_add_u64 v[158:159], s[50:51], 0, v[128:129]
	s_addc_u32 s19, s51, 0
	s_add_i32 s20, s21, s7
	global_load_lds_dwordx4 v[158:159], off
	v_lshl_add_u64 v[200:201], s[18:19], 0, v[132:133]
	s_mov_b32 m0, s20
	v_lshl_add_u64 v[222:223], s[60:61], 0, v[130:131]
	global_load_lds_dwordx4 v[200:201], off
	v_lshl_add_u64 v[200:201], s[18:19], 0, v[128:129]
	s_add_i32 m0, s20, 0x2000
	s_nop 0
	global_load_lds_dwordx4 v[200:201], off
	v_lshl_add_u64 v[200:201], s[60:61], 0, v[134:135]
	s_mov_b32 m0, s8
	s_nop 0
	global_load_lds_dwordx4 v[200:201], off
	s_mov_b32 m0, s9
	s_nop 0
	global_load_lds_dwordx4 v[222:223], off
	s_waitcnt vmcnt(8)
	s_waitcnt lgkmcnt(0)
	s_barrier
	s_setprio 1
	s_waitcnt lgkmcnt(0)
	v_mfma_f32_16x16x32_bf16 v[60:63], v[146:149], v[184:187], 0
	v_mfma_f32_16x16x32_bf16 v[56:59], v[154:157], v[184:187], 0
	v_mfma_f32_16x16x32_bf16 v[44:47], v[146:149], v[192:195], 0
	v_mfma_f32_16x16x32_bf16 v[40:43], v[154:157], v[192:195], 0
	v_mfma_f32_16x16x32_bf16 v[28:31], v[146:149], v[206:209], 0
	v_mfma_f32_16x16x32_bf16 v[24:27], v[154:157], v[206:209], 0
	v_mfma_f32_16x16x32_bf16 v[12:15], v[146:149], v[214:217], 0
	v_mfma_f32_16x16x32_bf16 v[8:11], v[154:157], v[214:217], 0
	v_mfma_f32_16x16x32_bf16 v[60:63], v[150:153], v[188:191], v[60:63]
	v_mfma_f32_16x16x32_bf16 v[56:59], v[164:167], v[188:191], v[56:59]
	v_mfma_f32_16x16x32_bf16 v[44:47], v[150:153], v[196:199], v[44:47]
	v_mfma_f32_16x16x32_bf16 v[40:43], v[164:167], v[196:199], v[40:43]
	v_mfma_f32_16x16x32_bf16 v[28:31], v[150:153], v[210:213], v[28:31]
	v_mfma_f32_16x16x32_bf16 v[24:27], v[164:167], v[210:213], v[24:27]
	v_mfma_f32_16x16x32_bf16 v[12:15], v[150:153], v[218:221], v[12:15]
	v_mfma_f32_16x16x32_bf16 v[8:11], v[164:167], v[218:221], v[8:11]
	s_setprio 0
	s_setprio 1
	v_mfma_f32_16x16x32_bf16 v[52:55], v[168:171], v[184:187], 0
	v_mfma_f32_16x16x32_bf16 v[48:51], v[176:179], v[184:187], 0
	v_mfma_f32_16x16x32_bf16 v[36:39], v[168:171], v[192:195], 0
	v_mfma_f32_16x16x32_bf16 v[32:35], v[176:179], v[192:195], 0
	v_mfma_f32_16x16x32_bf16 v[20:23], v[168:171], v[206:209], 0
	v_mfma_f32_16x16x32_bf16 v[16:19], v[176:179], v[206:209], 0
	v_mfma_f32_16x16x32_bf16 v[4:7], v[168:171], v[214:217], 0
	v_mfma_f32_16x16x32_bf16 v[0:3], v[176:179], v[214:217], 0
	v_mfma_f32_16x16x32_bf16 v[52:55], v[172:175], v[188:191], v[52:55]
	v_mfma_f32_16x16x32_bf16 v[48:51], v[180:183], v[188:191], v[48:51]
	v_mfma_f32_16x16x32_bf16 v[36:39], v[172:175], v[196:199], v[36:39]
	v_mfma_f32_16x16x32_bf16 v[32:35], v[180:183], v[196:199], v[32:35]
	v_mfma_f32_16x16x32_bf16 v[20:23], v[172:175], v[210:213], v[20:23]
	v_mfma_f32_16x16x32_bf16 v[16:19], v[180:183], v[210:213], v[16:19]
	v_mfma_f32_16x16x32_bf16 v[4:7], v[172:175], v[218:221], v[4:7]
	v_mfma_f32_16x16x32_bf16 v[0:3], v[180:183], v[218:221], v[0:3]
	s_setprio 0
	s_barrier
	s_add_i32 s20, 0, 0x18000
	v_add_u32_e32 v145, s20, v143
	s_add_i32 s21, 0, 0x1c000
	ds_read_b128 v[146:149], v145
	ds_read_b128 v[150:153], v145 offset:1024
	ds_read_b128 v[154:157], v145 offset:2048
	ds_read_b128 v[164:167], v145 offset:3072
	v_add_u32_e32 v145, s21, v143
	ds_read_b128 v[168:171], v145
	ds_read_b128 v[172:175], v145 offset:1024
	ds_read_b128 v[176:179], v145 offset:2048
	ds_read_b128 v[180:183], v145 offset:3072
	s_add_u32 s18, s60, 0x40000
	s_addc_u32 s19, s61, 0
	s_mov_b32 m0, s10
	v_lshl_add_u64 v[224:225], s[18:19], 0, v[134:135]
	ds_read_b128 v[184:187], v144 offset:32768
	ds_read_b128 v[188:191], v144 offset:33792
	ds_read_b128 v[192:195], v144 offset:34816
	ds_read_b128 v[196:199], v144 offset:35840
	ds_read_b128 v[206:209], v144 offset:36864
	ds_read_b128 v[210:213], v144 offset:37888
	ds_read_b128 v[214:217], v144 offset:38912
	ds_read_b128 v[218:221], v144 offset:39936
	global_load_lds_dwordx4 v[224:225], off
	v_lshl_add_u64 v[224:225], s[18:19], 0, v[130:131]
	s_mov_b32 m0, s11
	s_nop 0
	global_load_lds_dwordx4 v[224:225], off
	s_waitcnt vmcnt(8)
	s_waitcnt lgkmcnt(0)
	s_barrier
	s_setprio 1
	s_waitcnt lgkmcnt(0)
	v_mfma_f32_16x16x32_bf16 v[124:127], v[146:149], v[184:187], v[124:127]
	v_mfma_f32_16x16x32_bf16 v[120:123], v[154:157], v[184:187], v[120:123]
	v_mfma_f32_16x16x32_bf16 v[108:111], v[146:149], v[192:195], v[108:111]
	v_mfma_f32_16x16x32_bf16 v[104:107], v[154:157], v[192:195], v[104:107]
	v_mfma_f32_16x16x32_bf16 v[92:95], v[146:149], v[206:209], v[92:95]
	v_mfma_f32_16x16x32_bf16 v[88:91], v[154:157], v[206:209], v[88:91]
	v_mfma_f32_16x16x32_bf16 v[76:79], v[146:149], v[214:217], v[76:79]
	v_mfma_f32_16x16x32_bf16 v[72:75], v[154:157], v[214:217], v[72:75]
	v_mfma_f32_16x16x32_bf16 v[124:127], v[150:153], v[188:191], v[124:127]
	v_mfma_f32_16x16x32_bf16 v[120:123], v[164:167], v[188:191], v[120:123]
	v_mfma_f32_16x16x32_bf16 v[108:111], v[150:153], v[196:199], v[108:111]
	v_mfma_f32_16x16x32_bf16 v[104:107], v[164:167], v[196:199], v[104:107]
	v_mfma_f32_16x16x32_bf16 v[92:95], v[150:153], v[210:213], v[92:95]
	v_mfma_f32_16x16x32_bf16 v[88:91], v[164:167], v[210:213], v[88:91]
	v_mfma_f32_16x16x32_bf16 v[76:79], v[150:153], v[218:221], v[76:79]
	v_mfma_f32_16x16x32_bf16 v[72:75], v[164:167], v[218:221], v[72:75]
	s_setprio 0
	s_setprio 1
	v_mfma_f32_16x16x32_bf16 v[116:119], v[168:171], v[184:187], v[116:119]
	v_mfma_f32_16x16x32_bf16 v[112:115], v[176:179], v[184:187], v[112:115]
	v_mfma_f32_16x16x32_bf16 v[100:103], v[168:171], v[192:195], v[100:103]
	v_mfma_f32_16x16x32_bf16 v[96:99], v[176:179], v[192:195], v[96:99]
	v_mfma_f32_16x16x32_bf16 v[84:87], v[168:171], v[206:209], v[84:87]
	v_mfma_f32_16x16x32_bf16 v[80:83], v[176:179], v[206:209], v[80:83]
	v_mfma_f32_16x16x32_bf16 v[68:71], v[168:171], v[214:217], v[68:71]
	v_mfma_f32_16x16x32_bf16 v[64:67], v[176:179], v[214:217], v[64:67]
	v_mfma_f32_16x16x32_bf16 v[116:119], v[172:175], v[188:191], v[116:119]
	v_mfma_f32_16x16x32_bf16 v[112:115], v[180:183], v[188:191], v[112:115]
	v_mfma_f32_16x16x32_bf16 v[100:103], v[172:175], v[196:199], v[100:103]
	v_mfma_f32_16x16x32_bf16 v[96:99], v[180:183], v[196:199], v[96:99]
	v_mfma_f32_16x16x32_bf16 v[84:87], v[172:175], v[210:213], v[84:87]
	v_mfma_f32_16x16x32_bf16 v[80:83], v[180:183], v[210:213], v[80:83]
	v_mfma_f32_16x16x32_bf16 v[68:71], v[172:175], v[218:221], v[68:71]
	v_mfma_f32_16x16x32_bf16 v[64:67], v[180:183], v[218:221], v[64:67]
	s_setprio 0
	s_barrier
	s_add_i32 s18, s20, s7
	v_lshl_add_u64 v[140:141], v[140:141], 0, s[76:77]
	s_mov_b32 m0, s18
	ds_read_b128 v[184:187], v144 offset:49152
	ds_read_b128 v[188:191], v144 offset:50176
	ds_read_b128 v[192:195], v144 offset:51200
	ds_read_b128 v[196:199], v144 offset:52224
	ds_read_b128 v[206:209], v144 offset:53248
	ds_read_b128 v[210:213], v144 offset:54272
	ds_read_b128 v[214:217], v144 offset:55296
	ds_read_b128 v[218:221], v144 offset:56320
	global_load_lds_dwordx4 v[140:141], off
	s_add_i32 m0, s18, 0x2000
	s_add_u32 s18, s50, 0x40080
	v_lshl_add_u64 v[140:141], v[158:159], 0, s[76:77]
	s_addc_u32 s19, s51, 0
	s_add_i32 s20, s21, s7
	global_load_lds_dwordx4 v[140:141], off
	v_lshl_add_u64 v[140:141], s[18:19], 0, v[132:133]
	s_mov_b32 m0, s20
	s_nop 0
	global_load_lds_dwordx4 v[140:141], off
	v_lshl_add_u64 v[140:141], s[18:19], 0, v[128:129]
	s_add_i32 m0, s20, 0x2000
	s_nop 0
	global_load_lds_dwordx4 v[140:141], off
	v_lshl_add_u64 v[140:141], v[200:201], 0, s[76:77]
	s_mov_b32 m0, s12
	s_nop 0
	global_load_lds_dwordx4 v[140:141], off
	v_lshl_add_u64 v[140:141], v[222:223], 0, s[76:77]
	s_mov_b32 m0, s13
	s_nop 0
	global_load_lds_dwordx4 v[140:141], off
	s_waitcnt vmcnt(8)
	s_waitcnt lgkmcnt(0)
	s_barrier
	s_setprio 1
	s_waitcnt lgkmcnt(0)
	v_mfma_f32_16x16x32_bf16 v[60:63], v[146:149], v[184:187], v[60:63]
	v_mfma_f32_16x16x32_bf16 v[56:59], v[154:157], v[184:187], v[56:59]
	v_mfma_f32_16x16x32_bf16 v[44:47], v[146:149], v[192:195], v[44:47]
	v_mfma_f32_16x16x32_bf16 v[40:43], v[154:157], v[192:195], v[40:43]
	v_mfma_f32_16x16x32_bf16 v[28:31], v[146:149], v[206:209], v[28:31]
	v_mfma_f32_16x16x32_bf16 v[24:27], v[154:157], v[206:209], v[24:27]
	v_mfma_f32_16x16x32_bf16 v[12:15], v[146:149], v[214:217], v[12:15]
	v_mfma_f32_16x16x32_bf16 v[8:11], v[154:157], v[214:217], v[8:11]
	v_mfma_f32_16x16x32_bf16 v[60:63], v[150:153], v[188:191], v[60:63]
	v_mfma_f32_16x16x32_bf16 v[56:59], v[164:167], v[188:191], v[56:59]
	v_mfma_f32_16x16x32_bf16 v[44:47], v[150:153], v[196:199], v[44:47]
	v_mfma_f32_16x16x32_bf16 v[40:43], v[164:167], v[196:199], v[40:43]
	v_mfma_f32_16x16x32_bf16 v[28:31], v[150:153], v[210:213], v[28:31]
	v_mfma_f32_16x16x32_bf16 v[24:27], v[164:167], v[210:213], v[24:27]
	v_mfma_f32_16x16x32_bf16 v[12:15], v[150:153], v[218:221], v[12:15]
	v_mfma_f32_16x16x32_bf16 v[8:11], v[164:167], v[218:221], v[8:11]
	s_setprio 0
	s_setprio 1
	v_mfma_f32_16x16x32_bf16 v[52:55], v[168:171], v[184:187], v[52:55]
	v_mfma_f32_16x16x32_bf16 v[48:51], v[176:179], v[184:187], v[48:51]
	v_mfma_f32_16x16x32_bf16 v[36:39], v[168:171], v[192:195], v[36:39]
	v_mfma_f32_16x16x32_bf16 v[32:35], v[176:179], v[192:195], v[32:35]
	v_mfma_f32_16x16x32_bf16 v[20:23], v[168:171], v[206:209], v[20:23]
	v_mfma_f32_16x16x32_bf16 v[16:19], v[176:179], v[206:209], v[16:19]
	v_mfma_f32_16x16x32_bf16 v[4:7], v[168:171], v[214:217], v[4:7]
	v_mfma_f32_16x16x32_bf16 v[0:3], v[176:179], v[214:217], v[0:3]
	v_mfma_f32_16x16x32_bf16 v[52:55], v[172:175], v[188:191], v[52:55]
	v_mfma_f32_16x16x32_bf16 v[48:51], v[180:183], v[188:191], v[48:51]
	v_mfma_f32_16x16x32_bf16 v[36:39], v[172:175], v[196:199], v[36:39]
	v_mfma_f32_16x16x32_bf16 v[32:35], v[180:183], v[196:199], v[32:35]
	v_mfma_f32_16x16x32_bf16 v[20:23], v[172:175], v[210:213], v[20:23]
	v_mfma_f32_16x16x32_bf16 v[16:19], v[180:183], v[210:213], v[16:19]
	v_mfma_f32_16x16x32_bf16 v[4:7], v[172:175], v[218:221], v[4:7]
	v_mfma_f32_16x16x32_bf16 v[0:3], v[180:183], v[218:221], v[0:3]
	s_setprio 0
	s_add_i32 s63, s63, 2
	s_add_u32 s58, s58, 0x100
	s_addc_u32 s59, s59, 0
	s_add_u32 s47, s47, 0x100
	s_addc_u32 s62, s62, 0
	s_cmp_gt_u32 s63, 13
	s_cbranch_scc1 .Lrx_1138
	s_add_u32 s18, s58, 0xfffc0080
	s_addc_u32 s19, s59, -1
	s_add_i32 s20, 0, 0x10000
	s_cmp_eq_u32 s63, 12
	s_cselect_b32 s61, s17, s19
	s_cselect_b32 s60, s37, s18
	s_cselect_b32 s51, s39, s62
	s_cselect_b32 s50, s46, s47
	s_add_i32 s21, 0, 0x14000
	s_barrier
	s_branch .Lrot_1138
.Lrot_1138:
.LBB0_1138:
	v_add_u32_e32 v140, s20, v143
	ds_read_b128 v[146:149], v140
	ds_read_b128 v[150:153], v140 offset:1024
	ds_read_b128 v[154:157], v140 offset:2048
	ds_read_b128 v[164:167], v140 offset:3072
	v_add_u32_e32 v140, s21, v143
	ds_read_b128 v[168:171], v140
	ds_read_b128 v[172:175], v140 offset:1024
	ds_read_b128 v[176:179], v140 offset:2048
	ds_read_b128 v[180:183], v140 offset:3072
	v_lshl_add_u64 v[140:141], s[58:59], 0, v[136:137]
	s_add_i32 m0, s8, 0xc000
	ds_read_b128 v[184:187], v144
	ds_read_b128 v[188:191], v144 offset:1024
	ds_read_b128 v[192:195], v144 offset:2048
	ds_read_b128 v[196:199], v144 offset:3072
	ds_read_b128 v[206:209], v144 offset:4096
	ds_read_b128 v[210:213], v144 offset:5120
	ds_read_b128 v[214:217], v144 offset:6144
	ds_read_b128 v[218:221], v144 offset:7168
	global_load_lds_dwordx4 v[140:141], off
	v_lshl_add_u64 v[140:141], s[58:59], 0, v[138:139]
	s_add_i32 m0, s8, 0xe000
	s_nop 0
	global_load_lds_dwordx4 v[140:141], off
	s_waitcnt vmcnt(8)
	s_waitcnt lgkmcnt(0)
	s_barrier
	s_setprio 1
	s_waitcnt lgkmcnt(0)
	v_mfma_f32_16x16x32_bf16 v[124:127], v[146:149], v[184:187], v[124:127]
	v_mfma_f32_16x16x32_bf16 v[120:123], v[154:157], v[184:187], v[120:123]
	v_mfma_f32_16x16x32_bf16 v[108:111], v[146:149], v[192:195], v[108:111]
	v_mfma_f32_16x16x32_bf16 v[104:107], v[154:157], v[192:195], v[104:107]
	v_mfma_f32_16x16x32_bf16 v[92:95], v[146:149], v[206:209], v[92:95]
	v_mfma_f32_16x16x32_bf16 v[88:91], v[154:157], v[206:209], v[88:91]
	v_mfma_f32_16x16x32_bf16 v[76:79], v[146:149], v[214:217], v[76:79]
	v_mfma_f32_16x16x32_bf16 v[72:75], v[154:157], v[214:217], v[72:75]
	v_mfma_f32_16x16x32_bf16 v[124:127], v[150:153], v[188:191], v[124:127]
	v_mfma_f32_16x16x32_bf16 v[120:123], v[164:167], v[188:191], v[120:123]
	v_mfma_f32_16x16x32_bf16 v[108:111], v[150:153], v[196:199], v[108:111]
	v_mfma_f32_16x16x32_bf16 v[104:107], v[164:167], v[196:199], v[104:107]
	v_mfma_f32_16x16x32_bf16 v[92:95], v[150:153], v[210:213], v[92:95]
	v_mfma_f32_16x16x32_bf16 v[88:91], v[164:167], v[210:213], v[88:91]
	v_mfma_f32_16x16x32_bf16 v[76:79], v[150:153], v[218:221], v[76:79]
	v_mfma_f32_16x16x32_bf16 v[72:75], v[164:167], v[218:221], v[72:75]
	s_setprio 0
	s_setprio 1
	v_mfma_f32_16x16x32_bf16 v[116:119], v[168:171], v[184:187], v[116:119]
	v_mfma_f32_16x16x32_bf16 v[112:115], v[176:179], v[184:187], v[112:115]
	v_mfma_f32_16x16x32_bf16 v[100:103], v[168:171], v[192:195], v[100:103]
	v_mfma_f32_16x16x32_bf16 v[96:99], v[176:179], v[192:195], v[96:99]
	v_mfma_f32_16x16x32_bf16 v[84:87], v[168:171], v[206:209], v[84:87]
	v_mfma_f32_16x16x32_bf16 v[80:83], v[176:179], v[206:209], v[80:83]
	v_mfma_f32_16x16x32_bf16 v[68:71], v[168:171], v[214:217], v[68:71]
	v_mfma_f32_16x16x32_bf16 v[64:67], v[176:179], v[214:217], v[64:67]
	v_mfma_f32_16x16x32_bf16 v[116:119], v[172:175], v[188:191], v[116:119]
	v_mfma_f32_16x16x32_bf16 v[112:115], v[180:183], v[188:191], v[112:115]
	v_mfma_f32_16x16x32_bf16 v[100:103], v[172:175], v[196:199], v[100:103]
	v_mfma_f32_16x16x32_bf16 v[96:99], v[180:183], v[196:199], v[96:99]
	v_mfma_f32_16x16x32_bf16 v[84:87], v[172:175], v[210:213], v[84:87]
	v_mfma_f32_16x16x32_bf16 v[80:83], v[180:183], v[210:213], v[80:83]
	v_mfma_f32_16x16x32_bf16 v[68:71], v[172:175], v[218:221], v[68:71]
	v_mfma_f32_16x16x32_bf16 v[64:67], v[180:183], v[218:221], v[64:67]
	s_setprio 0
	s_barrier
	s_add_i32 s18, s20, s7
	v_lshl_add_u64 v[140:141], s[50:51], 0, v[132:133]
	s_mov_b32 m0, s18
	ds_read_b128 v[184:187], v144 offset:16384
	ds_read_b128 v[188:191], v144 offset:17408
	ds_read_b128 v[192:195], v144 offset:18432
	ds_read_b128 v[196:199], v144 offset:19456
	ds_read_b128 v[206:209], v144 offset:20480
	ds_read_b128 v[210:213], v144 offset:21504
	ds_read_b128 v[214:217], v144 offset:22528
	ds_read_b128 v[218:221], v144 offset:23552
	global_load_lds_dwordx4 v[140:141], off
	s_add_i32 m0, s18, 0x2000
	s_add_u32 s18, s50, 0x40000
	v_lshl_add_u64 v[158:159], s[50:51], 0, v[128:129]
	s_addc_u32 s19, s51, 0
	s_add_i32 s20, s21, s7
	global_load_lds_dwordx4 v[158:159], off
	v_lshl_add_u64 v[200:201], s[18:19], 0, v[132:133]
	s_mov_b32 m0, s20
	v_lshl_add_u64 v[222:223], s[60:61], 0, v[130:131]
	global_load_lds_dwordx4 v[200:201], off
	v_lshl_add_u64 v[200:201], s[18:19], 0, v[128:129]
	s_add_i32 m0, s20, 0x2000
	s_nop 0
	global_load_lds_dwordx4 v[200:201], off
	v_lshl_add_u64 v[200:201], s[60:61], 0, v[134:135]
	s_mov_b32 m0, s8
	s_nop 0
	global_load_lds_dwordx4 v[200:201], off
	s_mov_b32 m0, s9
	s_nop 0
	global_load_lds_dwordx4 v[222:223], off
	s_waitcnt vmcnt(8)
	s_waitcnt lgkmcnt(0)
	s_barrier
	s_setprio 1
	s_waitcnt lgkmcnt(0)
	v_mfma_f32_16x16x32_bf16 v[60:63], v[146:149], v[184:187], v[60:63]
	v_mfma_f32_16x16x32_bf16 v[56:59], v[154:157], v[184:187], v[56:59]
	v_mfma_f32_16x16x32_bf16 v[44:47], v[146:149], v[192:195], v[44:47]
	v_mfma_f32_16x16x32_bf16 v[40:43], v[154:157], v[192:195], v[40:43]
	v_mfma_f32_16x16x32_bf16 v[28:31], v[146:149], v[206:209], v[28:31]
	v_mfma_f32_16x16x32_bf16 v[24:27], v[154:157], v[206:209], v[24:27]
	v_mfma_f32_16x16x32_bf16 v[12:15], v[146:149], v[214:217], v[12:15]
	v_mfma_f32_16x16x32_bf16 v[8:11], v[154:157], v[214:217], v[8:11]
	v_mfma_f32_16x16x32_bf16 v[60:63], v[150:153], v[188:191], v[60:63]
	v_mfma_f32_16x16x32_bf16 v[56:59], v[164:167], v[188:191], v[56:59]
	v_mfma_f32_16x16x32_bf16 v[44:47], v[150:153], v[196:199], v[44:47]
	v_mfma_f32_16x16x32_bf16 v[40:43], v[164:167], v[196:199], v[40:43]
	v_mfma_f32_16x16x32_bf16 v[28:31], v[150:153], v[210:213], v[28:31]
	v_mfma_f32_16x16x32_bf16 v[24:27], v[164:167], v[210:213], v[24:27]
	v_mfma_f32_16x16x32_bf16 v[12:15], v[150:153], v[218:221], v[12:15]
	v_mfma_f32_16x16x32_bf16 v[8:11], v[164:167], v[218:221], v[8:11]
	s_setprio 0
	s_setprio 1
	v_mfma_f32_16x16x32_bf16 v[52:55], v[168:171], v[184:187], v[52:55]
	v_mfma_f32_16x16x32_bf16 v[48:51], v[176:179], v[184:187], v[48:51]
	v_mfma_f32_16x16x32_bf16 v[36:39], v[168:171], v[192:195], v[36:39]
	v_mfma_f32_16x16x32_bf16 v[32:35], v[176:179], v[192:195], v[32:35]
	v_mfma_f32_16x16x32_bf16 v[20:23], v[168:171], v[206:209], v[20:23]
	v_mfma_f32_16x16x32_bf16 v[16:19], v[176:179], v[206:209], v[16:19]
	v_mfma_f32_16x16x32_bf16 v[4:7], v[168:171], v[214:217], v[4:7]
	v_mfma_f32_16x16x32_bf16 v[0:3], v[176:179], v[214:217], v[0:3]
	v_mfma_f32_16x16x32_bf16 v[52:55], v[172:175], v[188:191], v[52:55]
	v_mfma_f32_16x16x32_bf16 v[48:51], v[180:183], v[188:191], v[48:51]
	v_mfma_f32_16x16x32_bf16 v[36:39], v[172:175], v[196:199], v[36:39]
	v_mfma_f32_16x16x32_bf16 v[32:35], v[180:183], v[196:199], v[32:35]
	v_mfma_f32_16x16x32_bf16 v[20:23], v[172:175], v[210:213], v[20:23]
	v_mfma_f32_16x16x32_bf16 v[16:19], v[180:183], v[210:213], v[16:19]
	v_mfma_f32_16x16x32_bf16 v[4:7], v[172:175], v[218:221], v[4:7]
	v_mfma_f32_16x16x32_bf16 v[0:3], v[180:183], v[218:221], v[0:3]
	s_setprio 0
	s_barrier
	s_add_i32 s20, 0, 0x18000
	v_add_u32_e32 v145, s20, v143
	s_add_i32 s21, 0, 0x1c000
	ds_read_b128 v[146:149], v145
	ds_read_b128 v[150:153], v145 offset:1024
	ds_read_b128 v[154:157], v145 offset:2048
	ds_read_b128 v[164:167], v145 offset:3072
	v_add_u32_e32 v145, s21, v143
	ds_read_b128 v[168:171], v145
	ds_read_b128 v[172:175], v145 offset:1024
	ds_read_b128 v[176:179], v145 offset:2048
	ds_read_b128 v[180:183], v145 offset:3072
	s_add_u32 s18, s60, 0x40000
	s_addc_u32 s19, s61, 0
	s_mov_b32 m0, s10
	v_lshl_add_u64 v[224:225], s[18:19], 0, v[134:135]
	ds_read_b128 v[184:187], v144 offset:32768
	ds_read_b128 v[188:191], v144 offset:33792
	ds_read_b128 v[192:195], v144 offset:34816
	ds_read_b128 v[196:199], v144 offset:35840
	ds_read_b128 v[206:209], v144 offset:36864
	ds_read_b128 v[210:213], v144 offset:37888
	ds_read_b128 v[214:217], v144 offset:38912
	ds_read_b128 v[218:221], v144 offset:39936
	global_load_lds_dwordx4 v[224:225], off
	v_lshl_add_u64 v[224:225], s[18:19], 0, v[130:131]
	s_mov_b32 m0, s11
	s_nop 0
	global_load_lds_dwordx4 v[224:225], off
	s_waitcnt vmcnt(8)
	s_waitcnt lgkmcnt(0)
	s_barrier
	s_setprio 1
	s_waitcnt lgkmcnt(0)
	v_mfma_f32_16x16x32_bf16 v[124:127], v[146:149], v[184:187], v[124:127]
	v_mfma_f32_16x16x32_bf16 v[120:123], v[154:157], v[184:187], v[120:123]
	v_mfma_f32_16x16x32_bf16 v[108:111], v[146:149], v[192:195], v[108:111]
	v_mfma_f32_16x16x32_bf16 v[104:107], v[154:157], v[192:195], v[104:107]
	v_mfma_f32_16x16x32_bf16 v[92:95], v[146:149], v[206:209], v[92:95]
	v_mfma_f32_16x16x32_bf16 v[88:91], v[154:157], v[206:209], v[88:91]
	v_mfma_f32_16x16x32_bf16 v[76:79], v[146:149], v[214:217], v[76:79]
	v_mfma_f32_16x16x32_bf16 v[72:75], v[154:157], v[214:217], v[72:75]
	v_mfma_f32_16x16x32_bf16 v[124:127], v[150:153], v[188:191], v[124:127]
	v_mfma_f32_16x16x32_bf16 v[120:123], v[164:167], v[188:191], v[120:123]
	v_mfma_f32_16x16x32_bf16 v[108:111], v[150:153], v[196:199], v[108:111]
	v_mfma_f32_16x16x32_bf16 v[104:107], v[164:167], v[196:199], v[104:107]
	v_mfma_f32_16x16x32_bf16 v[92:95], v[150:153], v[210:213], v[92:95]
	v_mfma_f32_16x16x32_bf16 v[88:91], v[164:167], v[210:213], v[88:91]
	v_mfma_f32_16x16x32_bf16 v[76:79], v[150:153], v[218:221], v[76:79]
	v_mfma_f32_16x16x32_bf16 v[72:75], v[164:167], v[218:221], v[72:75]
	s_setprio 0
	s_setprio 1
	v_mfma_f32_16x16x32_bf16 v[116:119], v[168:171], v[184:187], v[116:119]
	v_mfma_f32_16x16x32_bf16 v[112:115], v[176:179], v[184:187], v[112:115]
	v_mfma_f32_16x16x32_bf16 v[100:103], v[168:171], v[192:195], v[100:103]
	v_mfma_f32_16x16x32_bf16 v[96:99], v[176:179], v[192:195], v[96:99]
	v_mfma_f32_16x16x32_bf16 v[84:87], v[168:171], v[206:209], v[84:87]
	v_mfma_f32_16x16x32_bf16 v[80:83], v[176:179], v[206:209], v[80:83]
	v_mfma_f32_16x16x32_bf16 v[68:71], v[168:171], v[214:217], v[68:71]
	v_mfma_f32_16x16x32_bf16 v[64:67], v[176:179], v[214:217], v[64:67]
	v_mfma_f32_16x16x32_bf16 v[116:119], v[172:175], v[188:191], v[116:119]
	v_mfma_f32_16x16x32_bf16 v[112:115], v[180:183], v[188:191], v[112:115]
	v_mfma_f32_16x16x32_bf16 v[100:103], v[172:175], v[196:199], v[100:103]
	v_mfma_f32_16x16x32_bf16 v[96:99], v[180:183], v[196:199], v[96:99]
	v_mfma_f32_16x16x32_bf16 v[84:87], v[172:175], v[210:213], v[84:87]
	v_mfma_f32_16x16x32_bf16 v[80:83], v[180:183], v[210:213], v[80:83]
	v_mfma_f32_16x16x32_bf16 v[68:71], v[172:175], v[218:221], v[68:71]
	v_mfma_f32_16x16x32_bf16 v[64:67], v[180:183], v[218:221], v[64:67]
	s_setprio 0
	s_barrier
	s_add_i32 s18, s20, s7
	v_lshl_add_u64 v[140:141], v[140:141], 0, s[76:77]
	s_mov_b32 m0, s18
	ds_read_b128 v[184:187], v144 offset:49152
	ds_read_b128 v[188:191], v144 offset:50176
	ds_read_b128 v[192:195], v144 offset:51200
	ds_read_b128 v[196:199], v144 offset:52224
	ds_read_b128 v[206:209], v144 offset:53248
	ds_read_b128 v[210:213], v144 offset:54272
	ds_read_b128 v[214:217], v144 offset:55296
	ds_read_b128 v[218:221], v144 offset:56320
	global_load_lds_dwordx4 v[140:141], off
	s_add_i32 m0, s18, 0x2000
	s_add_u32 s18, s50, 0x40080
	v_lshl_add_u64 v[140:141], v[158:159], 0, s[76:77]
	s_addc_u32 s19, s51, 0
	s_add_i32 s20, s21, s7
	global_load_lds_dwordx4 v[140:141], off
	v_lshl_add_u64 v[140:141], s[18:19], 0, v[132:133]
	s_mov_b32 m0, s20
	s_nop 0
	global_load_lds_dwordx4 v[140:141], off
	v_lshl_add_u64 v[140:141], s[18:19], 0, v[128:129]
	s_add_i32 m0, s20, 0x2000
	s_nop 0
	global_load_lds_dwordx4 v[140:141], off
	v_lshl_add_u64 v[140:141], v[200:201], 0, s[76:77]
	s_mov_b32 m0, s12
	s_nop 0
	global_load_lds_dwordx4 v[140:141], off
	v_lshl_add_u64 v[140:141], v[222:223], 0, s[76:77]
	s_mov_b32 m0, s13
	s_nop 0
	global_load_lds_dwordx4 v[140:141], off
	s_waitcnt vmcnt(8)
	s_waitcnt lgkmcnt(0)
	s_barrier
	s_setprio 1
	s_waitcnt lgkmcnt(0)
	v_mfma_f32_16x16x32_bf16 v[60:63], v[146:149], v[184:187], v[60:63]
	v_mfma_f32_16x16x32_bf16 v[56:59], v[154:157], v[184:187], v[56:59]
	v_mfma_f32_16x16x32_bf16 v[44:47], v[146:149], v[192:195], v[44:47]
	v_mfma_f32_16x16x32_bf16 v[40:43], v[154:157], v[192:195], v[40:43]
	v_mfma_f32_16x16x32_bf16 v[28:31], v[146:149], v[206:209], v[28:31]
	v_mfma_f32_16x16x32_bf16 v[24:27], v[154:157], v[206:209], v[24:27]
	v_mfma_f32_16x16x32_bf16 v[12:15], v[146:149], v[214:217], v[12:15]
	v_mfma_f32_16x16x32_bf16 v[8:11], v[154:157], v[214:217], v[8:11]
	v_mfma_f32_16x16x32_bf16 v[60:63], v[150:153], v[188:191], v[60:63]
	v_mfma_f32_16x16x32_bf16 v[56:59], v[164:167], v[188:191], v[56:59]
	v_mfma_f32_16x16x32_bf16 v[44:47], v[150:153], v[196:199], v[44:47]
	v_mfma_f32_16x16x32_bf16 v[40:43], v[164:167], v[196:199], v[40:43]
	v_mfma_f32_16x16x32_bf16 v[28:31], v[150:153], v[210:213], v[28:31]
	v_mfma_f32_16x16x32_bf16 v[24:27], v[164:167], v[210:213], v[24:27]
	v_mfma_f32_16x16x32_bf16 v[12:15], v[150:153], v[218:221], v[12:15]
	v_mfma_f32_16x16x32_bf16 v[8:11], v[164:167], v[218:221], v[8:11]
	s_setprio 0
	s_setprio 1
	v_mfma_f32_16x16x32_bf16 v[52:55], v[168:171], v[184:187], v[52:55]
	v_mfma_f32_16x16x32_bf16 v[48:51], v[176:179], v[184:187], v[48:51]
	v_mfma_f32_16x16x32_bf16 v[36:39], v[168:171], v[192:195], v[36:39]
	v_mfma_f32_16x16x32_bf16 v[32:35], v[176:179], v[192:195], v[32:35]
	v_mfma_f32_16x16x32_bf16 v[20:23], v[168:171], v[206:209], v[20:23]
	v_mfma_f32_16x16x32_bf16 v[16:19], v[176:179], v[206:209], v[16:19]
	v_mfma_f32_16x16x32_bf16 v[4:7], v[168:171], v[214:217], v[4:7]
	v_mfma_f32_16x16x32_bf16 v[0:3], v[176:179], v[214:217], v[0:3]
	v_mfma_f32_16x16x32_bf16 v[52:55], v[172:175], v[188:191], v[52:55]
	v_mfma_f32_16x16x32_bf16 v[48:51], v[180:183], v[188:191], v[48:51]
	v_mfma_f32_16x16x32_bf16 v[36:39], v[172:175], v[196:199], v[36:39]
	v_mfma_f32_16x16x32_bf16 v[32:35], v[180:183], v[196:199], v[32:35]
	v_mfma_f32_16x16x32_bf16 v[20:23], v[172:175], v[210:213], v[20:23]
	v_mfma_f32_16x16x32_bf16 v[16:19], v[180:183], v[210:213], v[16:19]
	v_mfma_f32_16x16x32_bf16 v[4:7], v[172:175], v[218:221], v[4:7]
	v_mfma_f32_16x16x32_bf16 v[0:3], v[180:183], v[218:221], v[0:3]
	s_setprio 0
	s_add_i32 s63, s63, 2
	s_add_u32 s58, s58, 0x100
	s_addc_u32 s59, s59, 0
	s_add_u32 s47, s47, 0x100
	s_addc_u32 s62, s62, 0
	s_cmp_gt_u32 s63, 13
	s_cbranch_scc1 .Lrx_1138
	s_add_u32 s18, s58, 0xfffc0080
	s_addc_u32 s19, s59, -1
	s_add_i32 s20, 0, 0x10000
	s_cmp_eq_u32 s63, 12
	s_cselect_b32 s61, s17, s19
	s_cselect_b32 s60, s37, s18
	s_cselect_b32 s51, s39, s62
	s_cselect_b32 s50, s46, s47
	s_add_i32 s21, 0, 0x14000
	s_barrier
	s_branch .Lrot_1138
.Lrx_1138:
	s_barrier
.Lpeel_x_1138:
	s_and_b64 vcc, exec, s[2:3]
	s_cbranch_vccz .LBB0_1141
	s_barrier

.LBB0_1209:
	s_add_u32 s54, s48, 0x100
	s_addc_u32 s60, s49, 0
	s_mov_b32 s61, -2
	s_add_u32 s48, s42, 0x100
	s_addc_u32 s49, s43, 0
	s_add_i32 s18, 0, 0x10000
	s_cmp_eq_u32 s61, 40
	s_cselect_b32 s59, s39, s49
	s_cselect_b32 s58, s38, s48
	s_cselect_b32 s51, s41, s60
	s_cselect_b32 s50, s40, s54
	s_add_i32 s20, 0, 0x14000
	v_add_u32_e32 v140, s18, v174
	v_add_u32_e32 v162, s20, v174
	ds_read_b128 v[128:131], v140
	ds_read_b128 v[132:135], v140 offset:1024
	ds_read_b128 v[136:139], v140 offset:2048
	ds_read_b128 v[140:143], v140 offset:3072
	ds_read_b128 v[156:159], v162
	ds_read_b128 v[164:167], v162 offset:1024
	ds_read_b128 v[168:171], v162 offset:2048
	ds_read_b128 v[176:179], v162 offset:3072
	v_lshl_add_u64 v[200:201], s[42:43], 0, v[152:153]
	s_add_i32 m0, s4, 0xc000
	ds_read_b128 v[180:183], v175
	ds_read_b128 v[184:187], v175 offset:1024
	ds_read_b128 v[188:191], v175 offset:2048
	ds_read_b128 v[192:195], v175 offset:3072
	ds_read_b128 v[196:199], v175 offset:4096
	ds_read_b128 v[206:209], v175 offset:5120
	ds_read_b128 v[210:213], v175 offset:6144
	ds_read_b128 v[214:217], v175 offset:7168
	global_load_lds_dwordx4 v[200:201], off
	v_lshl_add_u64 v[200:201], s[42:43], 0, v[154:155]
	s_add_i32 m0, s4, 0xe000
	s_nop 0
	global_load_lds_dwordx4 v[200:201], off
	s_waitcnt vmcnt(8)
	s_waitcnt lgkmcnt(0)
	s_barrier
	s_setprio 1
	s_waitcnt lgkmcnt(0)
	v_mfma_f32_16x16x32_bf16 v[124:127], v[128:131], v[180:183], 0
	v_mfma_f32_16x16x32_bf16 v[120:123], v[136:139], v[180:183], 0
	v_mfma_f32_16x16x32_bf16 v[112:115], v[128:131], v[188:191], 0
	v_mfma_f32_16x16x32_bf16 v[104:107], v[136:139], v[188:191], 0
	v_mfma_f32_16x16x32_bf16 v[96:99], v[128:131], v[196:199], 0
	v_mfma_f32_16x16x32_bf16 v[88:91], v[136:139], v[196:199], 0
	v_mfma_f32_16x16x32_bf16 v[80:83], v[128:131], v[210:213], 0
	v_mfma_f32_16x16x32_bf16 v[72:75], v[136:139], v[210:213], 0
	v_mfma_f32_16x16x32_bf16 v[124:127], v[132:135], v[184:187], v[124:127]
	v_mfma_f32_16x16x32_bf16 v[120:123], v[140:143], v[184:187], v[120:123]
	v_mfma_f32_16x16x32_bf16 v[112:115], v[132:135], v[192:195], v[112:115]
	v_mfma_f32_16x16x32_bf16 v[104:107], v[140:143], v[192:195], v[104:107]
	v_mfma_f32_16x16x32_bf16 v[96:99], v[132:135], v[206:209], v[96:99]
	v_mfma_f32_16x16x32_bf16 v[88:91], v[140:143], v[206:209], v[88:91]
	v_mfma_f32_16x16x32_bf16 v[80:83], v[132:135], v[214:217], v[80:83]
	v_mfma_f32_16x16x32_bf16 v[72:75], v[140:143], v[214:217], v[72:75]
	s_setprio 0
	s_setprio 1
	v_mfma_f32_16x16x32_bf16 v[116:119], v[156:159], v[180:183], 0
	v_mfma_f32_16x16x32_bf16 v[108:111], v[168:171], v[180:183], 0
	v_mfma_f32_16x16x32_bf16 v[100:103], v[156:159], v[188:191], 0
	v_mfma_f32_16x16x32_bf16 v[92:95], v[168:171], v[188:191], 0
	v_mfma_f32_16x16x32_bf16 v[84:87], v[156:159], v[196:199], 0
	v_mfma_f32_16x16x32_bf16 v[76:79], v[168:171], v[196:199], 0
	v_mfma_f32_16x16x32_bf16 v[68:71], v[156:159], v[210:213], 0
	v_mfma_f32_16x16x32_bf16 v[64:67], v[168:171], v[210:213], 0
	v_mfma_f32_16x16x32_bf16 v[116:119], v[164:167], v[184:187], v[116:119]
	v_mfma_f32_16x16x32_bf16 v[108:111], v[176:179], v[184:187], v[108:111]
	v_mfma_f32_16x16x32_bf16 v[100:103], v[164:167], v[192:195], v[100:103]
	v_mfma_f32_16x16x32_bf16 v[92:95], v[176:179], v[192:195], v[92:95]
	v_mfma_f32_16x16x32_bf16 v[84:87], v[164:167], v[206:209], v[84:87]
	v_mfma_f32_16x16x32_bf16 v[76:79], v[176:179], v[206:209], v[76:79]
	v_mfma_f32_16x16x32_bf16 v[68:71], v[164:167], v[214:217], v[68:71]
	v_mfma_f32_16x16x32_bf16 v[64:67], v[176:179], v[214:217], v[64:67]
	s_setprio 0
	s_barrier
	s_add_i32 s18, s18, s46
	v_lshl_add_u64 v[200:201], s[50:51], 0, v[148:149]
	s_mov_b32 m0, s18
	ds_read_b128 v[180:183], v175 offset:16384
	ds_read_b128 v[184:187], v175 offset:17408
	ds_read_b128 v[188:191], v175 offset:18432
	ds_read_b128 v[192:195], v175 offset:19456
	ds_read_b128 v[196:199], v175 offset:20480
	ds_read_b128 v[206:209], v175 offset:21504
	ds_read_b128 v[210:213], v175 offset:22528
	ds_read_b128 v[214:217], v175 offset:23552
	global_load_lds_dwordx4 v[200:201], off
	s_add_i32 m0, s18, 0x2000
	s_add_u32 s18, s50, 0xb0000
	v_lshl_add_u64 v[218:219], s[50:51], 0, v[144:145]
	s_addc_u32 s19, s51, 0
	s_add_i32 s20, s20, s46
	global_load_lds_dwordx4 v[218:219], off
	v_lshl_add_u64 v[220:221], s[18:19], 0, v[148:149]
	s_mov_b32 m0, s20
	v_lshl_add_u64 v[222:223], s[58:59], 0, v[146:147]
	global_load_lds_dwordx4 v[220:221], off
	v_lshl_add_u64 v[220:221], s[18:19], 0, v[144:145]
	s_add_i32 m0, s20, 0x2000
	s_nop 0
	global_load_lds_dwordx4 v[220:221], off
	v_lshl_add_u64 v[220:221], s[58:59], 0, v[150:151]
	s_mov_b32 m0, s4
	s_nop 0
	global_load_lds_dwordx4 v[220:221], off
	s_mov_b32 m0, s5
	s_nop 0
	global_load_lds_dwordx4 v[222:223], off
	s_waitcnt vmcnt(8)
	s_waitcnt lgkmcnt(0)
	s_barrier
	s_setprio 1
	s_waitcnt lgkmcnt(0)
	v_mfma_f32_16x16x32_bf16 v[60:63], v[128:131], v[180:183], 0
	v_mfma_f32_16x16x32_bf16 v[56:59], v[136:139], v[180:183], 0
	v_mfma_f32_16x16x32_bf16 v[48:51], v[128:131], v[188:191], 0
	v_mfma_f32_16x16x32_bf16 v[40:43], v[136:139], v[188:191], 0
	v_mfma_f32_16x16x32_bf16 v[32:35], v[128:131], v[196:199], 0
	v_mfma_f32_16x16x32_bf16 v[24:27], v[136:139], v[196:199], 0
	v_mfma_f32_16x16x32_bf16 v[16:19], v[128:131], v[210:213], 0
	v_mfma_f32_16x16x32_bf16 v[8:11], v[136:139], v[210:213], 0
	v_mfma_f32_16x16x32_bf16 v[60:63], v[132:135], v[184:187], v[60:63]
	v_mfma_f32_16x16x32_bf16 v[56:59], v[140:143], v[184:187], v[56:59]
	v_mfma_f32_16x16x32_bf16 v[48:51], v[132:135], v[192:195], v[48:51]
	v_mfma_f32_16x16x32_bf16 v[40:43], v[140:143], v[192:195], v[40:43]
	v_mfma_f32_16x16x32_bf16 v[32:35], v[132:135], v[206:209], v[32:35]
	v_mfma_f32_16x16x32_bf16 v[24:27], v[140:143], v[206:209], v[24:27]
	v_mfma_f32_16x16x32_bf16 v[16:19], v[132:135], v[214:217], v[16:19]
	v_mfma_f32_16x16x32_bf16 v[8:11], v[140:143], v[214:217], v[8:11]
	s_setprio 0
	s_setprio 1
	v_mfma_f32_16x16x32_bf16 v[52:55], v[156:159], v[180:183], 0
	v_mfma_f32_16x16x32_bf16 v[44:47], v[168:171], v[180:183], 0
	v_mfma_f32_16x16x32_bf16 v[36:39], v[156:159], v[188:191], 0
	v_mfma_f32_16x16x32_bf16 v[28:31], v[168:171], v[188:191], 0
	v_mfma_f32_16x16x32_bf16 v[20:23], v[156:159], v[196:199], 0
	v_mfma_f32_16x16x32_bf16 v[12:15], v[168:171], v[196:199], 0
	v_mfma_f32_16x16x32_bf16 v[4:7], v[156:159], v[210:213], 0
	v_mfma_f32_16x16x32_bf16 v[0:3], v[168:171], v[210:213], 0
	v_mfma_f32_16x16x32_bf16 v[52:55], v[164:167], v[184:187], v[52:55]
	v_mfma_f32_16x16x32_bf16 v[44:47], v[176:179], v[184:187], v[44:47]
	v_mfma_f32_16x16x32_bf16 v[36:39], v[164:167], v[192:195], v[36:39]
	v_mfma_f32_16x16x32_bf16 v[28:31], v[176:179], v[192:195], v[28:31]
	v_mfma_f32_16x16x32_bf16 v[20:23], v[164:167], v[206:209], v[20:23]
	v_mfma_f32_16x16x32_bf16 v[12:15], v[176:179], v[206:209], v[12:15]
	v_mfma_f32_16x16x32_bf16 v[4:7], v[164:167], v[214:217], v[4:7]
	v_mfma_f32_16x16x32_bf16 v[0:3], v[176:179], v[214:217], v[0:3]
	s_setprio 0
	s_barrier
	s_add_i32 s20, 0, 0x18000
	s_add_i32 s21, 0, 0x1c000
	v_add_u32_e32 v140, s20, v174
	v_add_u32_e32 v162, s21, v174
	ds_read_b128 v[128:131], v140
	ds_read_b128 v[132:135], v140 offset:1024
	ds_read_b128 v[136:139], v140 offset:2048
	ds_read_b128 v[140:143], v140 offset:3072
	ds_read_b128 v[156:159], v162
	ds_read_b128 v[164:167], v162 offset:1024
	ds_read_b128 v[168:171], v162 offset:2048
	ds_read_b128 v[176:179], v162 offset:3072
	s_add_u32 s18, s58, 0xb0000
	s_addc_u32 s19, s59, 0
	s_mov_b32 m0, s6
	v_lshl_add_u64 v[224:225], s[18:19], 0, v[150:151]
	ds_read_b128 v[180:183], v175 offset:32768
	ds_read_b128 v[184:187], v175 offset:33792
	ds_read_b128 v[188:191], v175 offset:34816
	ds_read_b128 v[192:195], v175 offset:35840
	ds_read_b128 v[196:199], v175 offset:36864
	ds_read_b128 v[206:209], v175 offset:37888
	ds_read_b128 v[210:213], v175 offset:38912
	ds_read_b128 v[214:217], v175 offset:39936
	global_load_lds_dwordx4 v[224:225], off
	v_lshl_add_u64 v[224:225], s[18:19], 0, v[146:147]
	s_mov_b32 m0, s7
	s_nop 0
	global_load_lds_dwordx4 v[224:225], off
	s_waitcnt vmcnt(8)
	s_waitcnt lgkmcnt(0)
	s_barrier
	s_setprio 1
	s_waitcnt lgkmcnt(0)
	v_mfma_f32_16x16x32_bf16 v[124:127], v[128:131], v[180:183], v[124:127]
	v_mfma_f32_16x16x32_bf16 v[120:123], v[136:139], v[180:183], v[120:123]
	v_mfma_f32_16x16x32_bf16 v[112:115], v[128:131], v[188:191], v[112:115]
	v_mfma_f32_16x16x32_bf16 v[104:107], v[136:139], v[188:191], v[104:107]
	v_mfma_f32_16x16x32_bf16 v[96:99], v[128:131], v[196:199], v[96:99]
	v_mfma_f32_16x16x32_bf16 v[88:91], v[136:139], v[196:199], v[88:91]
	v_mfma_f32_16x16x32_bf16 v[80:83], v[128:131], v[210:213], v[80:83]
	v_mfma_f32_16x16x32_bf16 v[72:75], v[136:139], v[210:213], v[72:75]
	v_mfma_f32_16x16x32_bf16 v[124:127], v[132:135], v[184:187], v[124:127]
	v_mfma_f32_16x16x32_bf16 v[120:123], v[140:143], v[184:187], v[120:123]
	v_mfma_f32_16x16x32_bf16 v[112:115], v[132:135], v[192:195], v[112:115]
	v_mfma_f32_16x16x32_bf16 v[104:107], v[140:143], v[192:195], v[104:107]
	v_mfma_f32_16x16x32_bf16 v[96:99], v[132:135], v[206:209], v[96:99]
	v_mfma_f32_16x16x32_bf16 v[88:91], v[140:143], v[206:209], v[88:91]
	v_mfma_f32_16x16x32_bf16 v[80:83], v[132:135], v[214:217], v[80:83]
	v_mfma_f32_16x16x32_bf16 v[72:75], v[140:143], v[214:217], v[72:75]
	s_setprio 0
	s_setprio 1
	v_mfma_f32_16x16x32_bf16 v[116:119], v[156:159], v[180:183], v[116:119]
	v_mfma_f32_16x16x32_bf16 v[108:111], v[168:171], v[180:183], v[108:111]
	v_mfma_f32_16x16x32_bf16 v[100:103], v[156:159], v[188:191], v[100:103]
	v_mfma_f32_16x16x32_bf16 v[92:95], v[168:171], v[188:191], v[92:95]
	v_mfma_f32_16x16x32_bf16 v[84:87], v[156:159], v[196:199], v[84:87]
	v_mfma_f32_16x16x32_bf16 v[76:79], v[168:171], v[196:199], v[76:79]
	v_mfma_f32_16x16x32_bf16 v[68:71], v[156:159], v[210:213], v[68:71]
	v_mfma_f32_16x16x32_bf16 v[64:67], v[168:171], v[210:213], v[64:67]
	v_mfma_f32_16x16x32_bf16 v[116:119], v[164:167], v[184:187], v[116:119]
	v_mfma_f32_16x16x32_bf16 v[108:111], v[176:179], v[184:187], v[108:111]
	v_mfma_f32_16x16x32_bf16 v[100:103], v[164:167], v[192:195], v[100:103]
	v_mfma_f32_16x16x32_bf16 v[92:95], v[176:179], v[192:195], v[92:95]
	v_mfma_f32_16x16x32_bf16 v[84:87], v[164:167], v[206:209], v[84:87]
	v_mfma_f32_16x16x32_bf16 v[76:79], v[176:179], v[206:209], v[76:79]
	v_mfma_f32_16x16x32_bf16 v[68:71], v[164:167], v[214:217], v[68:71]
	v_mfma_f32_16x16x32_bf16 v[64:67], v[176:179], v[214:217], v[64:67]
	s_setprio 0
	s_barrier
	s_add_i32 s18, s20, s46
	v_lshl_add_u64 v[200:201], v[200:201], 0, s[76:77]
	s_mov_b32 m0, s18
	ds_read_b128 v[180:183], v175 offset:49152
	ds_read_b128 v[184:187], v175 offset:50176
	ds_read_b128 v[188:191], v175 offset:51200
	ds_read_b128 v[192:195], v175 offset:52224
	ds_read_b128 v[196:199], v175 offset:53248
	ds_read_b128 v[206:209], v175 offset:54272
	ds_read_b128 v[210:213], v175 offset:55296
	ds_read_b128 v[214:217], v175 offset:56320
	global_load_lds_dwordx4 v[200:201], off
	s_add_i32 m0, s18, 0x2000
	s_add_u32 s18, s50, 0xb0080
	v_lshl_add_u64 v[200:201], v[218:219], 0, s[76:77]
	s_addc_u32 s19, s51, 0
	s_add_i32 s20, s21, s46
	global_load_lds_dwordx4 v[200:201], off
	v_lshl_add_u64 v[200:201], s[18:19], 0, v[148:149]
	s_mov_b32 m0, s20
	s_nop 0
	global_load_lds_dwordx4 v[200:201], off
	v_lshl_add_u64 v[200:201], s[18:19], 0, v[144:145]
	s_add_i32 m0, s20, 0x2000
	s_nop 0
	global_load_lds_dwordx4 v[200:201], off
	v_lshl_add_u64 v[200:201], v[220:221], 0, s[76:77]
	s_mov_b32 m0, s11
	s_nop 0
	global_load_lds_dwordx4 v[200:201], off
	v_lshl_add_u64 v[200:201], v[222:223], 0, s[76:77]
	s_mov_b32 m0, s12
	s_nop 0
	global_load_lds_dwordx4 v[200:201], off
	s_waitcnt vmcnt(8)
	s_waitcnt lgkmcnt(0)
	s_barrier
	s_setprio 1
	s_waitcnt lgkmcnt(0)
	v_mfma_f32_16x16x32_bf16 v[60:63], v[128:131], v[180:183], v[60:63]
	v_mfma_f32_16x16x32_bf16 v[56:59], v[136:139], v[180:183], v[56:59]
	v_mfma_f32_16x16x32_bf16 v[48:51], v[128:131], v[188:191], v[48:51]
	v_mfma_f32_16x16x32_bf16 v[40:43], v[136:139], v[188:191], v[40:43]
	v_mfma_f32_16x16x32_bf16 v[32:35], v[128:131], v[196:199], v[32:35]
	v_mfma_f32_16x16x32_bf16 v[24:27], v[136:139], v[196:199], v[24:27]
	v_mfma_f32_16x16x32_bf16 v[16:19], v[128:131], v[210:213], v[16:19]
	v_mfma_f32_16x16x32_bf16 v[8:11], v[136:139], v[210:213], v[8:11]
	v_mfma_f32_16x16x32_bf16 v[60:63], v[132:135], v[184:187], v[60:63]
	v_mfma_f32_16x16x32_bf16 v[56:59], v[140:143], v[184:187], v[56:59]
	v_mfma_f32_16x16x32_bf16 v[48:51], v[132:135], v[192:195], v[48:51]
	v_mfma_f32_16x16x32_bf16 v[40:43], v[140:143], v[192:195], v[40:43]
	v_mfma_f32_16x16x32_bf16 v[32:35], v[132:135], v[206:209], v[32:35]
	v_mfma_f32_16x16x32_bf16 v[24:27], v[140:143], v[206:209], v[24:27]
	v_mfma_f32_16x16x32_bf16 v[16:19], v[132:135], v[214:217], v[16:19]
	v_mfma_f32_16x16x32_bf16 v[8:11], v[140:143], v[214:217], v[8:11]
	s_setprio 0
	s_setprio 1
	v_mfma_f32_16x16x32_bf16 v[52:55], v[156:159], v[180:183], v[52:55]
	v_mfma_f32_16x16x32_bf16 v[44:47], v[168:171], v[180:183], v[44:47]
	v_mfma_f32_16x16x32_bf16 v[36:39], v[156:159], v[188:191], v[36:39]
	v_mfma_f32_16x16x32_bf16 v[28:31], v[168:171], v[188:191], v[28:31]
	v_mfma_f32_16x16x32_bf16 v[20:23], v[156:159], v[196:199], v[20:23]
	v_mfma_f32_16x16x32_bf16 v[12:15], v[168:171], v[196:199], v[12:15]
	v_mfma_f32_16x16x32_bf16 v[4:7], v[156:159], v[210:213], v[4:7]
	v_mfma_f32_16x16x32_bf16 v[0:3], v[168:171], v[210:213], v[0:3]
	v_mfma_f32_16x16x32_bf16 v[52:55], v[164:167], v[184:187], v[52:55]
	v_mfma_f32_16x16x32_bf16 v[44:47], v[176:179], v[184:187], v[44:47]
	v_mfma_f32_16x16x32_bf16 v[36:39], v[164:167], v[192:195], v[36:39]
	v_mfma_f32_16x16x32_bf16 v[28:31], v[176:179], v[192:195], v[28:31]
	v_mfma_f32_16x16x32_bf16 v[20:23], v[164:167], v[206:209], v[20:23]
	v_mfma_f32_16x16x32_bf16 v[12:15], v[176:179], v[206:209], v[12:15]
	v_mfma_f32_16x16x32_bf16 v[4:7], v[164:167], v[214:217], v[4:7]
	v_mfma_f32_16x16x32_bf16 v[0:3], v[176:179], v[214:217], v[0:3]
	s_setprio 0
	s_add_i32 s61, s61, 2
	s_add_u32 s54, s54, 0x100
	s_addc_u32 s60, s60, 0
	s_mov_b64 s[42:43], s[48:49]
	s_cmp_gt_u32 s61, 41
	s_cbranch_scc1 .Lrx_1210
	s_add_u32 s48, s42, 0x100
	s_addc_u32 s49, s43, 0
	s_add_i32 s18, 0, 0x10000
	s_cmp_eq_u32 s61, 40
	s_cselect_b32 s59, s39, s49
	s_cselect_b32 s58, s38, s48
	s_cselect_b32 s51, s41, s60
	s_cselect_b32 s50, s40, s54
	s_add_i32 s20, 0, 0x14000
	s_barrier
	s_branch .Lrot_1210
.Lrot_1210:
.LBB0_1210:
	v_add_u32_e32 v140, s18, v174
	v_add_u32_e32 v162, s20, v174
	ds_read_b128 v[128:131], v140
	ds_read_b128 v[132:135], v140 offset:1024
	ds_read_b128 v[136:139], v140 offset:2048
	ds_read_b128 v[140:143], v140 offset:3072
	ds_read_b128 v[156:159], v162
	ds_read_b128 v[164:167], v162 offset:1024
	ds_read_b128 v[168:171], v162 offset:2048
	ds_read_b128 v[176:179], v162 offset:3072
	v_lshl_add_u64 v[200:201], s[42:43], 0, v[152:153]
	s_add_i32 m0, s4, 0xc000
	ds_read_b128 v[180:183], v175
	ds_read_b128 v[184:187], v175 offset:1024
	ds_read_b128 v[188:191], v175 offset:2048
	ds_read_b128 v[192:195], v175 offset:3072
	ds_read_b128 v[196:199], v175 offset:4096
	ds_read_b128 v[206:209], v175 offset:5120
	ds_read_b128 v[210:213], v175 offset:6144
	ds_read_b128 v[214:217], v175 offset:7168
	global_load_lds_dwordx4 v[200:201], off
	v_lshl_add_u64 v[200:201], s[42:43], 0, v[154:155]
	s_add_i32 m0, s4, 0xe000
	s_nop 0
	global_load_lds_dwordx4 v[200:201], off
	s_waitcnt vmcnt(8)
	s_waitcnt lgkmcnt(0)
	s_barrier
	s_setprio 1
	s_waitcnt lgkmcnt(0)
	v_mfma_f32_16x16x32_bf16 v[124:127], v[128:131], v[180:183], v[124:127]
	v_mfma_f32_16x16x32_bf16 v[120:123], v[136:139], v[180:183], v[120:123]
	v_mfma_f32_16x16x32_bf16 v[112:115], v[128:131], v[188:191], v[112:115]
	v_mfma_f32_16x16x32_bf16 v[104:107], v[136:139], v[188:191], v[104:107]
	v_mfma_f32_16x16x32_bf16 v[96:99], v[128:131], v[196:199], v[96:99]
	v_mfma_f32_16x16x32_bf16 v[88:91], v[136:139], v[196:199], v[88:91]
	v_mfma_f32_16x16x32_bf16 v[80:83], v[128:131], v[210:213], v[80:83]
	v_mfma_f32_16x16x32_bf16 v[72:75], v[136:139], v[210:213], v[72:75]
	v_mfma_f32_16x16x32_bf16 v[124:127], v[132:135], v[184:187], v[124:127]
	v_mfma_f32_16x16x32_bf16 v[120:123], v[140:143], v[184:187], v[120:123]
	v_mfma_f32_16x16x32_bf16 v[112:115], v[132:135], v[192:195], v[112:115]
	v_mfma_f32_16x16x32_bf16 v[104:107], v[140:143], v[192:195], v[104:107]
	v_mfma_f32_16x16x32_bf16 v[96:99], v[132:135], v[206:209], v[96:99]
	v_mfma_f32_16x16x32_bf16 v[88:91], v[140:143], v[206:209], v[88:91]
	v_mfma_f32_16x16x32_bf16 v[80:83], v[132:135], v[214:217], v[80:83]
	v_mfma_f32_16x16x32_bf16 v[72:75], v[140:143], v[214:217], v[72:75]
	s_setprio 0
	s_setprio 1
	v_mfma_f32_16x16x32_bf16 v[116:119], v[156:159], v[180:183], v[116:119]
	v_mfma_f32_16x16x32_bf16 v[108:111], v[168:171], v[180:183], v[108:111]
	v_mfma_f32_16x16x32_bf16 v[100:103], v[156:159], v[188:191], v[100:103]
	v_mfma_f32_16x16x32_bf16 v[92:95], v[168:171], v[188:191], v[92:95]
	v_mfma_f32_16x16x32_bf16 v[84:87], v[156:159], v[196:199], v[84:87]
	v_mfma_f32_16x16x32_bf16 v[76:79], v[168:171], v[196:199], v[76:79]
	v_mfma_f32_16x16x32_bf16 v[68:71], v[156:159], v[210:213], v[68:71]
	v_mfma_f32_16x16x32_bf16 v[64:67], v[168:171], v[210:213], v[64:67]
	v_mfma_f32_16x16x32_bf16 v[116:119], v[164:167], v[184:187], v[116:119]
	v_mfma_f32_16x16x32_bf16 v[108:111], v[176:179], v[184:187], v[108:111]
	v_mfma_f32_16x16x32_bf16 v[100:103], v[164:167], v[192:195], v[100:103]
	v_mfma_f32_16x16x32_bf16 v[92:95], v[176:179], v[192:195], v[92:95]
	v_mfma_f32_16x16x32_bf16 v[84:87], v[164:167], v[206:209], v[84:87]
	v_mfma_f32_16x16x32_bf16 v[76:79], v[176:179], v[206:209], v[76:79]
	v_mfma_f32_16x16x32_bf16 v[68:71], v[164:167], v[214:217], v[68:71]
	v_mfma_f32_16x16x32_bf16 v[64:67], v[176:179], v[214:217], v[64:67]
	s_setprio 0
	s_barrier
	s_add_i32 s18, s18, s46
	v_lshl_add_u64 v[200:201], s[50:51], 0, v[148:149]
	s_mov_b32 m0, s18
	ds_read_b128 v[180:183], v175 offset:16384
	ds_read_b128 v[184:187], v175 offset:17408
	ds_read_b128 v[188:191], v175 offset:18432
	ds_read_b128 v[192:195], v175 offset:19456
	ds_read_b128 v[196:199], v175 offset:20480
	ds_read_b128 v[206:209], v175 offset:21504
	ds_read_b128 v[210:213], v175 offset:22528
	ds_read_b128 v[214:217], v175 offset:23552
	global_load_lds_dwordx4 v[200:201], off
	s_add_i32 m0, s18, 0x2000
	s_add_u32 s18, s50, 0xb0000
	v_lshl_add_u64 v[218:219], s[50:51], 0, v[144:145]
	s_addc_u32 s19, s51, 0
	s_add_i32 s20, s20, s46
	global_load_lds_dwordx4 v[218:219], off
	v_lshl_add_u64 v[220:221], s[18:19], 0, v[148:149]
	s_mov_b32 m0, s20
	v_lshl_add_u64 v[222:223], s[58:59], 0, v[146:147]
	global_load_lds_dwordx4 v[220:221], off
	v_lshl_add_u64 v[220:221], s[18:19], 0, v[144:145]
	s_add_i32 m0, s20, 0x2000
	s_nop 0
	global_load_lds_dwordx4 v[220:221], off
	v_lshl_add_u64 v[220:221], s[58:59], 0, v[150:151]
	s_mov_b32 m0, s4
	s_nop 0
	global_load_lds_dwordx4 v[220:221], off
	s_mov_b32 m0, s5
	s_nop 0
	global_load_lds_dwordx4 v[222:223], off
	s_waitcnt vmcnt(8)
	s_waitcnt lgkmcnt(0)
	s_barrier
	s_setprio 1
	s_waitcnt lgkmcnt(0)
	v_mfma_f32_16x16x32_bf16 v[60:63], v[128:131], v[180:183], v[60:63]
	v_mfma_f32_16x16x32_bf16 v[56:59], v[136:139], v[180:183], v[56:59]
	v_mfma_f32_16x16x32_bf16 v[48:51], v[128:131], v[188:191], v[48:51]
	v_mfma_f32_16x16x32_bf16 v[40:43], v[136:139], v[188:191], v[40:43]
	v_mfma_f32_16x16x32_bf16 v[32:35], v[128:131], v[196:199], v[32:35]
	v_mfma_f32_16x16x32_bf16 v[24:27], v[136:139], v[196:199], v[24:27]
	v_mfma_f32_16x16x32_bf16 v[16:19], v[128:131], v[210:213], v[16:19]
	v_mfma_f32_16x16x32_bf16 v[8:11], v[136:139], v[210:213], v[8:11]
	v_mfma_f32_16x16x32_bf16 v[60:63], v[132:135], v[184:187], v[60:63]
	v_mfma_f32_16x16x32_bf16 v[56:59], v[140:143], v[184:187], v[56:59]
	v_mfma_f32_16x16x32_bf16 v[48:51], v[132:135], v[192:195], v[48:51]
	v_mfma_f32_16x16x32_bf16 v[40:43], v[140:143], v[192:195], v[40:43]
	v_mfma_f32_16x16x32_bf16 v[32:35], v[132:135], v[206:209], v[32:35]
	v_mfma_f32_16x16x32_bf16 v[24:27], v[140:143], v[206:209], v[24:27]
	v_mfma_f32_16x16x32_bf16 v[16:19], v[132:135], v[214:217], v[16:19]
	v_mfma_f32_16x16x32_bf16 v[8:11], v[140:143], v[214:217], v[8:11]
	s_setprio 0
	s_setprio 1
	v_mfma_f32_16x16x32_bf16 v[52:55], v[156:159], v[180:183], v[52:55]
	v_mfma_f32_16x16x32_bf16 v[44:47], v[168:171], v[180:183], v[44:47]
	v_mfma_f32_16x16x32_bf16 v[36:39], v[156:159], v[188:191], v[36:39]
	v_mfma_f32_16x16x32_bf16 v[28:31], v[168:171], v[188:191], v[28:31]
	v_mfma_f32_16x16x32_bf16 v[20:23], v[156:159], v[196:199], v[20:23]
	v_mfma_f32_16x16x32_bf16 v[12:15], v[168:171], v[196:199], v[12:15]
	v_mfma_f32_16x16x32_bf16 v[4:7], v[156:159], v[210:213], v[4:7]
	v_mfma_f32_16x16x32_bf16 v[0:3], v[168:171], v[210:213], v[0:3]
	v_mfma_f32_16x16x32_bf16 v[52:55], v[164:167], v[184:187], v[52:55]
	v_mfma_f32_16x16x32_bf16 v[44:47], v[176:179], v[184:187], v[44:47]
	v_mfma_f32_16x16x32_bf16 v[36:39], v[164:167], v[192:195], v[36:39]
	v_mfma_f32_16x16x32_bf16 v[28:31], v[176:179], v[192:195], v[28:31]
	v_mfma_f32_16x16x32_bf16 v[20:23], v[164:167], v[206:209], v[20:23]
	v_mfma_f32_16x16x32_bf16 v[12:15], v[176:179], v[206:209], v[12:15]
	v_mfma_f32_16x16x32_bf16 v[4:7], v[164:167], v[214:217], v[4:7]
	v_mfma_f32_16x16x32_bf16 v[0:3], v[176:179], v[214:217], v[0:3]
	s_setprio 0
	s_barrier
	s_add_i32 s20, 0, 0x18000
	s_add_i32 s21, 0, 0x1c000
	v_add_u32_e32 v140, s20, v174
	v_add_u32_e32 v162, s21, v174
	ds_read_b128 v[128:131], v140
	ds_read_b128 v[132:135], v140 offset:1024
	ds_read_b128 v[136:139], v140 offset:2048
	ds_read_b128 v[140:143], v140 offset:3072
	ds_read_b128 v[156:159], v162
	ds_read_b128 v[164:167], v162 offset:1024
	ds_read_b128 v[168:171], v162 offset:2048
	ds_read_b128 v[176:179], v162 offset:3072
	s_add_u32 s18, s58, 0xb0000
	s_addc_u32 s19, s59, 0
	s_mov_b32 m0, s6
	v_lshl_add_u64 v[224:225], s[18:19], 0, v[150:151]
	ds_read_b128 v[180:183], v175 offset:32768
	ds_read_b128 v[184:187], v175 offset:33792
	ds_read_b128 v[188:191], v175 offset:34816
	ds_read_b128 v[192:195], v175 offset:35840
	ds_read_b128 v[196:199], v175 offset:36864
	ds_read_b128 v[206:209], v175 offset:37888
	ds_read_b128 v[210:213], v175 offset:38912
	ds_read_b128 v[214:217], v175 offset:39936
	global_load_lds_dwordx4 v[224:225], off
	v_lshl_add_u64 v[224:225], s[18:19], 0, v[146:147]
	s_mov_b32 m0, s7
	s_nop 0
	global_load_lds_dwordx4 v[224:225], off
	s_waitcnt vmcnt(8)
	s_waitcnt lgkmcnt(0)
	s_barrier
	s_setprio 1
	s_waitcnt lgkmcnt(0)
	v_mfma_f32_16x16x32_bf16 v[124:127], v[128:131], v[180:183], v[124:127]
	v_mfma_f32_16x16x32_bf16 v[120:123], v[136:139], v[180:183], v[120:123]
	v_mfma_f32_16x16x32_bf16 v[112:115], v[128:131], v[188:191], v[112:115]
	v_mfma_f32_16x16x32_bf16 v[104:107], v[136:139], v[188:191], v[104:107]
	v_mfma_f32_16x16x32_bf16 v[96:99], v[128:131], v[196:199], v[96:99]
	v_mfma_f32_16x16x32_bf16 v[88:91], v[136:139], v[196:199], v[88:91]
	v_mfma_f32_16x16x32_bf16 v[80:83], v[128:131], v[210:213], v[80:83]
	v_mfma_f32_16x16x32_bf16 v[72:75], v[136:139], v[210:213], v[72:75]
	v_mfma_f32_16x16x32_bf16 v[124:127], v[132:135], v[184:187], v[124:127]
	v_mfma_f32_16x16x32_bf16 v[120:123], v[140:143], v[184:187], v[120:123]
	v_mfma_f32_16x16x32_bf16 v[112:115], v[132:135], v[192:195], v[112:115]
	v_mfma_f32_16x16x32_bf16 v[104:107], v[140:143], v[192:195], v[104:107]
	v_mfma_f32_16x16x32_bf16 v[96:99], v[132:135], v[206:209], v[96:99]
	v_mfma_f32_16x16x32_bf16 v[88:91], v[140:143], v[206:209], v[88:91]
	v_mfma_f32_16x16x32_bf16 v[80:83], v[132:135], v[214:217], v[80:83]
	v_mfma_f32_16x16x32_bf16 v[72:75], v[140:143], v[214:217], v[72:75]
	s_setprio 0
	s_setprio 1
	v_mfma_f32_16x16x32_bf16 v[116:119], v[156:159], v[180:183], v[116:119]
	v_mfma_f32_16x16x32_bf16 v[108:111], v[168:171], v[180:183], v[108:111]
	v_mfma_f32_16x16x32_bf16 v[100:103], v[156:159], v[188:191], v[100:103]
	v_mfma_f32_16x16x32_bf16 v[92:95], v[168:171], v[188:191], v[92:95]
	v_mfma_f32_16x16x32_bf16 v[84:87], v[156:159], v[196:199], v[84:87]
	v_mfma_f32_16x16x32_bf16 v[76:79], v[168:171], v[196:199], v[76:79]
	v_mfma_f32_16x16x32_bf16 v[68:71], v[156:159], v[210:213], v[68:71]
	v_mfma_f32_16x16x32_bf16 v[64:67], v[168:171], v[210:213], v[64:67]
	v_mfma_f32_16x16x32_bf16 v[116:119], v[164:167], v[184:187], v[116:119]
	v_mfma_f32_16x16x32_bf16 v[108:111], v[176:179], v[184:187], v[108:111]
	v_mfma_f32_16x16x32_bf16 v[100:103], v[164:167], v[192:195], v[100:103]
	v_mfma_f32_16x16x32_bf16 v[92:95], v[176:179], v[192:195], v[92:95]
	v_mfma_f32_16x16x32_bf16 v[84:87], v[164:167], v[206:209], v[84:87]
	v_mfma_f32_16x16x32_bf16 v[76:79], v[176:179], v[206:209], v[76:79]
	v_mfma_f32_16x16x32_bf16 v[68:71], v[164:167], v[214:217], v[68:71]
	v_mfma_f32_16x16x32_bf16 v[64:67], v[176:179], v[214:217], v[64:67]
	s_setprio 0
	s_barrier
	s_add_i32 s18, s20, s46
	v_lshl_add_u64 v[200:201], v[200:201], 0, s[76:77]
	s_mov_b32 m0, s18
	ds_read_b128 v[180:183], v175 offset:49152
	ds_read_b128 v[184:187], v175 offset:50176
	ds_read_b128 v[188:191], v175 offset:51200
	ds_read_b128 v[192:195], v175 offset:52224
	ds_read_b128 v[196:199], v175 offset:53248
	ds_read_b128 v[206:209], v175 offset:54272
	ds_read_b128 v[210:213], v175 offset:55296
	ds_read_b128 v[214:217], v175 offset:56320
	global_load_lds_dwordx4 v[200:201], off
	s_add_i32 m0, s18, 0x2000
	s_add_u32 s18, s50, 0xb0080
	v_lshl_add_u64 v[200:201], v[218:219], 0, s[76:77]
	s_addc_u32 s19, s51, 0
	s_add_i32 s20, s21, s46
	global_load_lds_dwordx4 v[200:201], off
	v_lshl_add_u64 v[200:201], s[18:19], 0, v[148:149]
	s_mov_b32 m0, s20
	s_nop 0
	global_load_lds_dwordx4 v[200:201], off
	v_lshl_add_u64 v[200:201], s[18:19], 0, v[144:145]
	s_add_i32 m0, s20, 0x2000
	s_nop 0
	global_load_lds_dwordx4 v[200:201], off
	v_lshl_add_u64 v[200:201], v[220:221], 0, s[76:77]
	s_mov_b32 m0, s11
	s_nop 0
	global_load_lds_dwordx4 v[200:201], off
	v_lshl_add_u64 v[200:201], v[222:223], 0, s[76:77]
	s_mov_b32 m0, s12
	s_nop 0
	global_load_lds_dwordx4 v[200:201], off
	s_waitcnt vmcnt(8)
	s_waitcnt lgkmcnt(0)
	s_barrier
	s_setprio 1
	s_waitcnt lgkmcnt(0)
	v_mfma_f32_16x16x32_bf16 v[60:63], v[128:131], v[180:183], v[60:63]
	v_mfma_f32_16x16x32_bf16 v[56:59], v[136:139], v[180:183], v[56:59]
	v_mfma_f32_16x16x32_bf16 v[48:51], v[128:131], v[188:191], v[48:51]
	v_mfma_f32_16x16x32_bf16 v[40:43], v[136:139], v[188:191], v[40:43]
	v_mfma_f32_16x16x32_bf16 v[32:35], v[128:131], v[196:199], v[32:35]
	v_mfma_f32_16x16x32_bf16 v[24:27], v[136:139], v[196:199], v[24:27]
	v_mfma_f32_16x16x32_bf16 v[16:19], v[128:131], v[210:213], v[16:19]
	v_mfma_f32_16x16x32_bf16 v[8:11], v[136:139], v[210:213], v[8:11]
	v_mfma_f32_16x16x32_bf16 v[60:63], v[132:135], v[184:187], v[60:63]
	v_mfma_f32_16x16x32_bf16 v[56:59], v[140:143], v[184:187], v[56:59]
	v_mfma_f32_16x16x32_bf16 v[48:51], v[132:135], v[192:195], v[48:51]
	v_mfma_f32_16x16x32_bf16 v[40:43], v[140:143], v[192:195], v[40:43]
	v_mfma_f32_16x16x32_bf16 v[32:35], v[132:135], v[206:209], v[32:35]
	v_mfma_f32_16x16x32_bf16 v[24:27], v[140:143], v[206:209], v[24:27]
	v_mfma_f32_16x16x32_bf16 v[16:19], v[132:135], v[214:217], v[16:19]
	v_mfma_f32_16x16x32_bf16 v[8:11], v[140:143], v[214:217], v[8:11]
	s_setprio 0
	s_setprio 1
	v_mfma_f32_16x16x32_bf16 v[52:55], v[156:159], v[180:183], v[52:55]
	v_mfma_f32_16x16x32_bf16 v[44:47], v[168:171], v[180:183], v[44:47]
	v_mfma_f32_16x16x32_bf16 v[36:39], v[156:159], v[188:191], v[36:39]
	v_mfma_f32_16x16x32_bf16 v[28:31], v[168:171], v[188:191], v[28:31]
	v_mfma_f32_16x16x32_bf16 v[20:23], v[156:159], v[196:199], v[20:23]
	v_mfma_f32_16x16x32_bf16 v[12:15], v[168:171], v[196:199], v[12:15]
	v_mfma_f32_16x16x32_bf16 v[4:7], v[156:159], v[210:213], v[4:7]
	v_mfma_f32_16x16x32_bf16 v[0:3], v[168:171], v[210:213], v[0:3]
	v_mfma_f32_16x16x32_bf16 v[52:55], v[164:167], v[184:187], v[52:55]
	v_mfma_f32_16x16x32_bf16 v[44:47], v[176:179], v[184:187], v[44:47]
	v_mfma_f32_16x16x32_bf16 v[36:39], v[164:167], v[192:195], v[36:39]
	v_mfma_f32_16x16x32_bf16 v[28:31], v[176:179], v[192:195], v[28:31]
	v_mfma_f32_16x16x32_bf16 v[20:23], v[164:167], v[206:209], v[20:23]
	v_mfma_f32_16x16x32_bf16 v[12:15], v[176:179], v[206:209], v[12:15]
	v_mfma_f32_16x16x32_bf16 v[4:7], v[164:167], v[214:217], v[4:7]
	v_mfma_f32_16x16x32_bf16 v[0:3], v[176:179], v[214:217], v[0:3]
	s_setprio 0
	s_add_i32 s61, s61, 2
	s_add_u32 s54, s54, 0x100
	s_addc_u32 s60, s60, 0
	s_mov_b64 s[42:43], s[48:49]
	s_cmp_gt_u32 s61, 41
	s_cbranch_scc1 .Lrx_1210
	s_add_u32 s48, s42, 0x100
	s_addc_u32 s49, s43, 0
	s_add_i32 s18, 0, 0x10000
	s_cmp_eq_u32 s61, 40
	s_cselect_b32 s59, s39, s49
	s_cselect_b32 s58, s38, s48
	s_cselect_b32 s51, s41, s60
	s_cselect_b32 s50, s40, s54
	s_add_i32 s20, 0, 0x14000
	s_barrier
	s_branch .Lrot_1210
.Lrx_1210:
	s_barrier
.Lpeel_x_1210:
	s_and_b64 vcc, exec, s[2:3]
	s_cbranch_vccz .LBB0_1213
	s_barrier
